# in-loop copy slots only (one per K-iteration in the gate/up and down-projection loops, 37.5 percent of the plain-copy units, no epilogue copies) plus all the instruction-level trims of v29
# speedup vs baseline: 1.0044x; 1.0044x over previous
.LBB0_1658:
	ds_read_b128 v[152:155], v149
	ds_read_b128 v[156:159], v149 offset:1024
	ds_read_b128 v[160:163], v149 offset:2048
	ds_read_b128 v[166:169], v149 offset:3072
	ds_read_b128 v[170:173], v150
	ds_read_b128 v[174:177], v150 offset:1024
	ds_read_b128 v[178:181], v150 offset:2048
	ds_read_b128 v[182:185], v150 offset:3072
	s_add_u32 s50, s58, 0xfffc0080
	s_addc_u32 s51, s59, -1
	s_cmp_eq_u32 s49, 12
	s_cselect_b32 s63, s33, s51
	s_cselect_b32 s62, s34, s50
	s_cselect_b32 s61, s37, s48
	s_cselect_b32 s60, s39, s42
	v_lshl_add_u64 v[218:219], s[58:59], 0, v[140:141]
	s_add_i32 m0, s18, 0xc000
	ds_read_b128 v[186:189], v151
	ds_read_b128 v[190:193], v151 offset:1024
	ds_read_b128 v[194:197], v151 offset:2048
	ds_read_b128 v[198:201], v151 offset:3072
	ds_read_b128 v[202:205], v151 offset:4096
	ds_read_b128 v[206:209], v151 offset:5120
	ds_read_b128 v[210:213], v151 offset:6144
	ds_read_b128 v[214:217], v151 offset:7168
	global_load_lds_dwordx4 v[218:219], off
	v_lshl_add_u64 v[218:219], s[58:59], 0, v[142:143]
	s_add_i32 m0, s18, 0xe000
	s_nop 0
	global_load_lds_dwordx4 v[218:219], off
	s_waitcnt vmcnt(9)
	s_waitcnt lgkmcnt(0)
	s_barrier
	s_setprio 1
	v_mfma_f32_16x16x32_bf16 v[124:127], v[152:155], v[186:189], v[124:127]
	v_mfma_f32_16x16x32_bf16 v[120:123], v[160:163], v[186:189], v[120:123]
	v_mfma_f32_16x16x32_bf16 v[108:111], v[152:155], v[194:197], v[108:111]
	v_mfma_f32_16x16x32_bf16 v[104:107], v[160:163], v[194:197], v[104:107]
	v_mfma_f32_16x16x32_bf16 v[92:95], v[152:155], v[202:205], v[92:95]
	v_mfma_f32_16x16x32_bf16 v[88:91], v[160:163], v[202:205], v[88:91]
	v_mfma_f32_16x16x32_bf16 v[76:79], v[152:155], v[210:213], v[76:79]
	v_mfma_f32_16x16x32_bf16 v[72:75], v[160:163], v[210:213], v[72:75]
	v_mfma_f32_16x16x32_bf16 v[124:127], v[156:159], v[190:193], v[124:127]
	v_mfma_f32_16x16x32_bf16 v[120:123], v[166:169], v[190:193], v[120:123]
	v_mfma_f32_16x16x32_bf16 v[108:111], v[156:159], v[198:201], v[108:111]
	v_mfma_f32_16x16x32_bf16 v[104:107], v[166:169], v[198:201], v[104:107]
	v_mfma_f32_16x16x32_bf16 v[92:95], v[156:159], v[206:209], v[92:95]
	v_mfma_f32_16x16x32_bf16 v[88:91], v[166:169], v[206:209], v[88:91]
	v_mfma_f32_16x16x32_bf16 v[76:79], v[156:159], v[214:217], v[76:79]
	v_mfma_f32_16x16x32_bf16 v[72:75], v[166:169], v[214:217], v[72:75]
	v_mfma_f32_16x16x32_bf16 v[116:119], v[170:173], v[186:189], v[116:119]
	v_mfma_f32_16x16x32_bf16 v[112:115], v[178:181], v[186:189], v[112:115]
	v_mfma_f32_16x16x32_bf16 v[100:103], v[170:173], v[194:197], v[100:103]
	v_mfma_f32_16x16x32_bf16 v[96:99], v[178:181], v[194:197], v[96:99]
	v_mfma_f32_16x16x32_bf16 v[84:87], v[170:173], v[202:205], v[84:87]
	v_mfma_f32_16x16x32_bf16 v[80:83], v[178:181], v[202:205], v[80:83]
	v_mfma_f32_16x16x32_bf16 v[68:71], v[170:173], v[210:213], v[68:71]
	v_mfma_f32_16x16x32_bf16 v[64:67], v[178:181], v[210:213], v[64:67]
	v_mfma_f32_16x16x32_bf16 v[116:119], v[174:177], v[190:193], v[116:119]
	v_mfma_f32_16x16x32_bf16 v[112:115], v[182:185], v[190:193], v[112:115]
	v_mfma_f32_16x16x32_bf16 v[100:103], v[174:177], v[198:201], v[100:103]
	v_mfma_f32_16x16x32_bf16 v[96:99], v[182:185], v[198:201], v[96:99]
	v_mfma_f32_16x16x32_bf16 v[84:87], v[174:177], v[206:209], v[84:87]
	v_mfma_f32_16x16x32_bf16 v[80:83], v[182:185], v[206:209], v[80:83]
	v_mfma_f32_16x16x32_bf16 v[68:71], v[174:177], v[214:217], v[68:71]
	v_mfma_f32_16x16x32_bf16 v[64:67], v[182:185], v[214:217], v[64:67]
	s_setprio 0
	s_barrier
	s_add_i32 s50, s64, s3
	v_lshl_add_u64 v[218:219], s[60:61], 0, v[134:135]
	s_mov_b32 m0, s50
	ds_read_b128 v[186:189], v151 offset:16384
	ds_read_b128 v[190:193], v151 offset:17408
	ds_read_b128 v[194:197], v151 offset:18432
	ds_read_b128 v[198:201], v151 offset:19456
	ds_read_b128 v[202:205], v151 offset:20480
	ds_read_b128 v[206:209], v151 offset:21504
	ds_read_b128 v[210:213], v151 offset:22528
	ds_read_b128 v[214:217], v151 offset:23552
	global_load_lds_dwordx4 v[218:219], off
	s_add_i32 m0, s50, 0x2000
	s_add_u32 s50, s60, 0x40000
	v_lshl_add_u64 v[220:221], s[60:61], 0, v[130:131]
	s_addc_u32 s51, s61, 0
	s_add_i32 s57, s65, s3
	global_load_lds_dwordx4 v[220:221], off
	v_lshl_add_u64 v[222:223], s[50:51], 0, v[134:135]
	s_mov_b32 m0, s57
	v_lshl_add_u64 v[224:225], s[62:63], 0, v[132:133]
	global_load_lds_dwordx4 v[222:223], off
	v_lshl_add_u64 v[222:223], s[50:51], 0, v[130:131]
	s_add_i32 m0, s57, 0x2000
	s_nop 0
	global_load_lds_dwordx4 v[222:223], off
	v_lshl_add_u64 v[222:223], s[62:63], 0, v[136:137]
	s_mov_b32 m0, s18
	s_nop 0
	global_load_lds_dwordx4 v[222:223], off
	s_mov_b32 m0, s19
	s_nop 0
	global_load_lds_dwordx4 v[224:225], off
	s_waitcnt vmcnt(8)
	s_waitcnt lgkmcnt(0)
	s_barrier
	s_setprio 1
	v_mfma_f32_16x16x32_bf16 v[60:63], v[152:155], v[186:189], v[60:63]
	v_mfma_f32_16x16x32_bf16 v[56:59], v[160:163], v[186:189], v[56:59]
	v_mfma_f32_16x16x32_bf16 v[44:47], v[152:155], v[194:197], v[44:47]
	v_mfma_f32_16x16x32_bf16 v[40:43], v[160:163], v[194:197], v[40:43]
	v_mfma_f32_16x16x32_bf16 v[28:31], v[152:155], v[202:205], v[28:31]
	v_mfma_f32_16x16x32_bf16 v[24:27], v[160:163], v[202:205], v[24:27]
	v_mfma_f32_16x16x32_bf16 v[12:15], v[152:155], v[210:213], v[12:15]
	v_mfma_f32_16x16x32_bf16 v[8:11], v[160:163], v[210:213], v[8:11]
	v_mfma_f32_16x16x32_bf16 v[60:63], v[156:159], v[190:193], v[60:63]
	v_mfma_f32_16x16x32_bf16 v[56:59], v[166:169], v[190:193], v[56:59]
	v_mfma_f32_16x16x32_bf16 v[44:47], v[156:159], v[198:201], v[44:47]
	v_mfma_f32_16x16x32_bf16 v[40:43], v[166:169], v[198:201], v[40:43]
	v_mfma_f32_16x16x32_bf16 v[28:31], v[156:159], v[206:209], v[28:31]
	v_mfma_f32_16x16x32_bf16 v[24:27], v[166:169], v[206:209], v[24:27]
	v_mfma_f32_16x16x32_bf16 v[12:15], v[156:159], v[214:217], v[12:15]
	v_mfma_f32_16x16x32_bf16 v[8:11], v[166:169], v[214:217], v[8:11]
	v_mfma_f32_16x16x32_bf16 v[52:55], v[170:173], v[186:189], v[52:55]
	v_mfma_f32_16x16x32_bf16 v[48:51], v[178:181], v[186:189], v[48:51]
	v_mfma_f32_16x16x32_bf16 v[36:39], v[170:173], v[194:197], v[36:39]
	v_mfma_f32_16x16x32_bf16 v[32:35], v[178:181], v[194:197], v[32:35]
	v_mfma_f32_16x16x32_bf16 v[20:23], v[170:173], v[202:205], v[20:23]
	v_mfma_f32_16x16x32_bf16 v[16:19], v[178:181], v[202:205], v[16:19]
	v_mfma_f32_16x16x32_bf16 v[4:7], v[170:173], v[210:213], v[4:7]
	v_mfma_f32_16x16x32_bf16 v[0:3], v[178:181], v[210:213], v[0:3]
	v_mfma_f32_16x16x32_bf16 v[52:55], v[174:177], v[190:193], v[52:55]
	v_mfma_f32_16x16x32_bf16 v[48:51], v[182:185], v[190:193], v[48:51]
	v_mfma_f32_16x16x32_bf16 v[36:39], v[174:177], v[198:201], v[36:39]
	v_mfma_f32_16x16x32_bf16 v[32:35], v[182:185], v[198:201], v[32:35]
	v_mfma_f32_16x16x32_bf16 v[20:23], v[174:177], v[206:209], v[20:23]
	v_mfma_f32_16x16x32_bf16 v[16:19], v[182:185], v[206:209], v[16:19]
	v_mfma_f32_16x16x32_bf16 v[4:7], v[174:177], v[214:217], v[4:7]
	v_mfma_f32_16x16x32_bf16 v[0:3], v[182:185], v[214:217], v[0:3]
	s_setprio 0
	s_barrier
	buffer_store_dwordx4 v[228:231], v246, s[76:79], s101 offen offset:0 nt
	s_add_i32 s57, 0, 0x18000
	v_add_u32_e32 v165, s57, v148
	s_add_i32 s68, 0, 0x1c000
	ds_read_b128 v[152:155], v165
	ds_read_b128 v[156:159], v165 offset:1024
	ds_read_b128 v[160:163], v165 offset:2048
	ds_read_b128 v[166:169], v165 offset:3072
	v_add_u32_e32 v165, s68, v148
	ds_read_b128 v[170:173], v165
	ds_read_b128 v[174:177], v165 offset:1024
	ds_read_b128 v[178:181], v165 offset:2048
	ds_read_b128 v[182:185], v165 offset:3072
	s_add_u32 s50, s62, 0x40000
	s_addc_u32 s51, s63, 0
	s_mov_b32 m0, s35
	v_lshl_add_u64 v[226:227], s[50:51], 0, v[136:137]
	ds_read_b128 v[186:189], v151 offset:32768
	ds_read_b128 v[190:193], v151 offset:33792
	ds_read_b128 v[194:197], v151 offset:34816
	ds_read_b128 v[198:201], v151 offset:35840
	ds_read_b128 v[202:205], v151 offset:36864
	ds_read_b128 v[206:209], v151 offset:37888
	ds_read_b128 v[210:213], v151 offset:38912
	ds_read_b128 v[214:217], v151 offset:39936
	global_load_lds_dwordx4 v[226:227], off
	v_lshl_add_u64 v[226:227], s[50:51], 0, v[132:133]
	s_mov_b32 m0, s43
	s_nop 0
	global_load_lds_dwordx4 v[226:227], off
	buffer_load_dwordx4 v[228:231], v246, s[96:99], s100 offen offset:0 nt
	s_waitcnt vmcnt(10)
	s_waitcnt lgkmcnt(0)
	s_barrier
	s_setprio 1
	v_mfma_f32_16x16x32_bf16 v[124:127], v[152:155], v[186:189], v[124:127]
	v_mfma_f32_16x16x32_bf16 v[120:123], v[160:163], v[186:189], v[120:123]
	v_mfma_f32_16x16x32_bf16 v[108:111], v[152:155], v[194:197], v[108:111]
	v_mfma_f32_16x16x32_bf16 v[104:107], v[160:163], v[194:197], v[104:107]
	v_mfma_f32_16x16x32_bf16 v[92:95], v[152:155], v[202:205], v[92:95]
	v_mfma_f32_16x16x32_bf16 v[88:91], v[160:163], v[202:205], v[88:91]
	v_mfma_f32_16x16x32_bf16 v[76:79], v[152:155], v[210:213], v[76:79]
	v_mfma_f32_16x16x32_bf16 v[72:75], v[160:163], v[210:213], v[72:75]
	v_mfma_f32_16x16x32_bf16 v[124:127], v[156:159], v[190:193], v[124:127]
	v_mfma_f32_16x16x32_bf16 v[120:123], v[166:169], v[190:193], v[120:123]
	v_mfma_f32_16x16x32_bf16 v[108:111], v[156:159], v[198:201], v[108:111]
	v_mfma_f32_16x16x32_bf16 v[104:107], v[166:169], v[198:201], v[104:107]
	v_mfma_f32_16x16x32_bf16 v[92:95], v[156:159], v[206:209], v[92:95]
	v_mfma_f32_16x16x32_bf16 v[88:91], v[166:169], v[206:209], v[88:91]
	v_mfma_f32_16x16x32_bf16 v[76:79], v[156:159], v[214:217], v[76:79]
	v_mfma_f32_16x16x32_bf16 v[72:75], v[166:169], v[214:217], v[72:75]
	v_mfma_f32_16x16x32_bf16 v[116:119], v[170:173], v[186:189], v[116:119]
	v_mfma_f32_16x16x32_bf16 v[112:115], v[178:181], v[186:189], v[112:115]
	v_mfma_f32_16x16x32_bf16 v[100:103], v[170:173], v[194:197], v[100:103]
	v_mfma_f32_16x16x32_bf16 v[96:99], v[178:181], v[194:197], v[96:99]
	v_mfma_f32_16x16x32_bf16 v[84:87], v[170:173], v[202:205], v[84:87]
	v_mfma_f32_16x16x32_bf16 v[80:83], v[178:181], v[202:205], v[80:83]
	v_mfma_f32_16x16x32_bf16 v[68:71], v[170:173], v[210:213], v[68:71]
	v_mfma_f32_16x16x32_bf16 v[64:67], v[178:181], v[210:213], v[64:67]
	v_mfma_f32_16x16x32_bf16 v[116:119], v[174:177], v[190:193], v[116:119]
	v_mfma_f32_16x16x32_bf16 v[112:115], v[182:185], v[190:193], v[112:115]
	v_mfma_f32_16x16x32_bf16 v[100:103], v[174:177], v[198:201], v[100:103]
	v_mfma_f32_16x16x32_bf16 v[96:99], v[182:185], v[198:201], v[96:99]
	v_mfma_f32_16x16x32_bf16 v[84:87], v[174:177], v[206:209], v[84:87]
	v_mfma_f32_16x16x32_bf16 v[80:83], v[182:185], v[206:209], v[80:83]
	v_mfma_f32_16x16x32_bf16 v[68:71], v[174:177], v[214:217], v[68:71]
	v_mfma_f32_16x16x32_bf16 v[64:67], v[182:185], v[214:217], v[64:67]
	s_setprio 0
	s_barrier
	s_add_i32 s50, s57, s3
	v_lshl_add_u64 v[218:219], v[218:219], 0, s[24:25]
	s_mov_b32 m0, s50
	ds_read_b128 v[186:189], v151 offset:49152
	ds_read_b128 v[190:193], v151 offset:50176
	ds_read_b128 v[194:197], v151 offset:51200
	ds_read_b128 v[198:201], v151 offset:52224
	ds_read_b128 v[202:205], v151 offset:53248
	ds_read_b128 v[206:209], v151 offset:54272
	ds_read_b128 v[210:213], v151 offset:55296
	ds_read_b128 v[214:217], v151 offset:56320
	global_load_lds_dwordx4 v[218:219], off
	s_add_i32 m0, s50, 0x2000
	s_add_u32 s50, s60, 0x40080
	v_lshl_add_u64 v[218:219], v[220:221], 0, s[24:25]
	s_addc_u32 s51, s61, 0
	s_add_i32 s57, s68, s3
	global_load_lds_dwordx4 v[218:219], off
	v_lshl_add_u64 v[218:219], s[50:51], 0, v[134:135]
	s_mov_b32 m0, s57
	s_nop 0
	global_load_lds_dwordx4 v[218:219], off
	v_lshl_add_u64 v[218:219], s[50:51], 0, v[130:131]
	s_add_i32 m0, s57, 0x2000
	s_nop 0
	global_load_lds_dwordx4 v[218:219], off
	v_lshl_add_u64 v[218:219], v[222:223], 0, s[24:25]
	s_mov_b32 m0, s44
	s_nop 0
	global_load_lds_dwordx4 v[218:219], off
	v_lshl_add_u64 v[218:219], v[224:225], 0, s[24:25]
	s_mov_b32 m0, s45
	s_nop 0
	global_load_lds_dwordx4 v[218:219], off
	s_waitcnt vmcnt(10)
	s_waitcnt lgkmcnt(0)
	s_barrier
	s_setprio 1
	v_mfma_f32_16x16x32_bf16 v[60:63], v[152:155], v[186:189], v[60:63]
	v_mfma_f32_16x16x32_bf16 v[56:59], v[160:163], v[186:189], v[56:59]
	v_mfma_f32_16x16x32_bf16 v[44:47], v[152:155], v[194:197], v[44:47]
	v_mfma_f32_16x16x32_bf16 v[40:43], v[160:163], v[194:197], v[40:43]
	v_mfma_f32_16x16x32_bf16 v[28:31], v[152:155], v[202:205], v[28:31]
	v_mfma_f32_16x16x32_bf16 v[24:27], v[160:163], v[202:205], v[24:27]
	v_mfma_f32_16x16x32_bf16 v[12:15], v[152:155], v[210:213], v[12:15]
	v_mfma_f32_16x16x32_bf16 v[8:11], v[160:163], v[210:213], v[8:11]
	v_mfma_f32_16x16x32_bf16 v[60:63], v[156:159], v[190:193], v[60:63]
	v_mfma_f32_16x16x32_bf16 v[56:59], v[166:169], v[190:193], v[56:59]
	v_mfma_f32_16x16x32_bf16 v[44:47], v[156:159], v[198:201], v[44:47]
	v_mfma_f32_16x16x32_bf16 v[40:43], v[166:169], v[198:201], v[40:43]
	v_mfma_f32_16x16x32_bf16 v[28:31], v[156:159], v[206:209], v[28:31]
	v_mfma_f32_16x16x32_bf16 v[24:27], v[166:169], v[206:209], v[24:27]
	v_mfma_f32_16x16x32_bf16 v[12:15], v[156:159], v[214:217], v[12:15]
	v_mfma_f32_16x16x32_bf16 v[8:11], v[166:169], v[214:217], v[8:11]
	v_mfma_f32_16x16x32_bf16 v[52:55], v[170:173], v[186:189], v[52:55]
	v_mfma_f32_16x16x32_bf16 v[48:51], v[178:181], v[186:189], v[48:51]
	v_mfma_f32_16x16x32_bf16 v[36:39], v[170:173], v[194:197], v[36:39]
	v_mfma_f32_16x16x32_bf16 v[32:35], v[178:181], v[194:197], v[32:35]
	v_mfma_f32_16x16x32_bf16 v[20:23], v[170:173], v[202:205], v[20:23]
	v_mfma_f32_16x16x32_bf16 v[16:19], v[178:181], v[202:205], v[16:19]
	v_mfma_f32_16x16x32_bf16 v[4:7], v[170:173], v[210:213], v[4:7]
	v_mfma_f32_16x16x32_bf16 v[0:3], v[178:181], v[210:213], v[0:3]
	v_mfma_f32_16x16x32_bf16 v[52:55], v[174:177], v[190:193], v[52:55]
	v_mfma_f32_16x16x32_bf16 v[48:51], v[182:185], v[190:193], v[48:51]
	v_mfma_f32_16x16x32_bf16 v[36:39], v[174:177], v[198:201], v[36:39]
	v_mfma_f32_16x16x32_bf16 v[32:35], v[182:185], v[198:201], v[32:35]
	v_mfma_f32_16x16x32_bf16 v[20:23], v[174:177], v[206:209], v[20:23]
	v_mfma_f32_16x16x32_bf16 v[16:19], v[182:185], v[206:209], v[16:19]
	v_mfma_f32_16x16x32_bf16 v[4:7], v[174:177], v[214:217], v[4:7]
	v_mfma_f32_16x16x32_bf16 v[0:3], v[182:185], v[214:217], v[0:3]
	s_sub_u32 s4, s4, 1
	s_cmp_eq_u32 s4, 0
	s_cselect_b32 s100, 0x70000000, s100
	s_mov_b32 s101, s100
	s_add_i32 s32, s32, 1
	s_cmp_eq_u32 s32, 12
	s_cselect_b32 vcc_lo, 0x3000, 0
	s_cselect_b32 s32, 0, s32
	s_add_u32 s100, s100, vcc_lo
	s_addk_i32 s100, 0x400
	s_add_i32 s49, s49, 2
	s_add_u32 s58, s58, 0x100
	s_addc_u32 s59, s59, 0
	s_add_u32 s42, s42, 0x100
	s_addc_u32 s48, s48, 0
	s_cmp_gt_u32 s49, 13
	s_setprio 0
	s_barrier
	s_cbranch_scc0 .LBB0_1658
	s_and_b64 vcc, exec, s[26:27]
	s_cbranch_vccz .LBB0_1661
	s_barrier
